# static s_setprio 1 for waves 4-7 in P1/P10 K loops, per-phase priority flips removed (on top of W2-in-tail)
# speedup vs baseline: 1.0047x; 1.0047x over previous
.LBB0_276:
	s_and_b64 s[30:31], s[20:21], exec
	s_cselect_b32 s2, s17, s27
	s_cselect_b32 s13, s16, s26
	s_cselect_b32 s15, s19, s29
	s_cselect_b32 s23, s18, s28
	s_add_u32 s26, s26, 0x80080
	s_addc_u32 s27, s27, 0
	s_add_u32 s25, s28, 0x100
	v_mov_b32_e32 v2, 0
	s_addc_u32 s33, s29, 0
	s_mov_b32 s50, -2
	v_mov_b32_e32 v3, v2
	v_mov_b32_e32 v4, v2
	v_mov_b32_e32 v5, v2
	v_mov_b32_e32 v6, v2
	v_mov_b32_e32 v7, v2
	v_mov_b32_e32 v8, v2
	v_mov_b32_e32 v9, v2
	v_mov_b32_e32 v18, v2
	v_mov_b32_e32 v19, v2
	v_mov_b32_e32 v20, v2
	v_mov_b32_e32 v21, v2
	v_mov_b32_e32 v22, v2
	v_mov_b32_e32 v23, v2
	v_mov_b32_e32 v24, v2
	v_mov_b32_e32 v25, v2
	v_mov_b32_e32 v34, v2
	v_mov_b32_e32 v35, v2
	v_mov_b32_e32 v36, v2
	v_mov_b32_e32 v37, v2
	v_mov_b32_e32 v38, v2
	v_mov_b32_e32 v39, v2
	v_mov_b32_e32 v40, v2
	v_mov_b32_e32 v41, v2
	v_mov_b32_e32 v50, v2
	v_mov_b32_e32 v51, v2
	v_mov_b32_e32 v52, v2
	v_mov_b32_e32 v53, v2
	v_mov_b32_e32 v54, v2
	v_mov_b32_e32 v55, v2
	v_mov_b32_e32 v56, v2
	v_mov_b32_e32 v57, v2
	v_mov_b32_e32 v10, v2
	v_mov_b32_e32 v11, v2
	v_mov_b32_e32 v12, v2
	v_mov_b32_e32 v13, v2
	v_mov_b32_e32 v14, v2
	v_mov_b32_e32 v15, v2
	v_mov_b32_e32 v16, v2
	v_mov_b32_e32 v17, v2
	v_mov_b32_e32 v26, v2
	v_mov_b32_e32 v27, v2
	v_mov_b32_e32 v28, v2
	v_mov_b32_e32 v29, v2
	v_mov_b32_e32 v30, v2
	v_mov_b32_e32 v31, v2
	v_mov_b32_e32 v32, v2
	v_mov_b32_e32 v33, v2
	v_mov_b32_e32 v42, v2
	v_mov_b32_e32 v43, v2
	v_mov_b32_e32 v44, v2
	v_mov_b32_e32 v45, v2
	v_mov_b32_e32 v46, v2
	v_mov_b32_e32 v47, v2
	v_mov_b32_e32 v48, v2
	v_mov_b32_e32 v49, v2
	v_mov_b32_e32 v58, v2
	v_mov_b32_e32 v59, v2
	v_mov_b32_e32 v60, v2
	v_mov_b32_e32 v61, v2
	v_mov_b32_e32 v62, v2
	v_mov_b32_e32 v63, v2
	v_mov_b32_e32 v64, v2
	v_mov_b32_e32 v65, v2
	v_mov_b32_e32 v66, v2
	v_mov_b32_e32 v67, v2
	v_mov_b32_e32 v68, v2
	v_mov_b32_e32 v69, v2
	v_mov_b32_e32 v70, v2
	v_mov_b32_e32 v71, v2
	v_mov_b32_e32 v72, v2
	v_mov_b32_e32 v73, v2
	v_mov_b32_e32 v82, v2
	v_mov_b32_e32 v83, v2
	v_mov_b32_e32 v84, v2
	v_mov_b32_e32 v85, v2
	v_mov_b32_e32 v86, v2
	v_mov_b32_e32 v87, v2
	v_mov_b32_e32 v88, v2
	v_mov_b32_e32 v89, v2
	v_mov_b32_e32 v98, v2
	v_mov_b32_e32 v99, v2
	v_mov_b32_e32 v100, v2
	v_mov_b32_e32 v101, v2
	v_mov_b32_e32 v102, v2
	v_mov_b32_e32 v103, v2
	v_mov_b32_e32 v104, v2
	v_mov_b32_e32 v105, v2
	v_mov_b32_e32 v114, v2
	v_mov_b32_e32 v115, v2
	v_mov_b32_e32 v116, v2
	v_mov_b32_e32 v117, v2
	v_mov_b32_e32 v118, v2
	v_mov_b32_e32 v119, v2
	v_mov_b32_e32 v120, v2
	v_mov_b32_e32 v121, v2
	v_mov_b32_e32 v74, v2
	v_mov_b32_e32 v75, v2
	v_mov_b32_e32 v76, v2
	v_mov_b32_e32 v77, v2
	v_mov_b32_e32 v78, v2
	v_mov_b32_e32 v79, v2
	v_mov_b32_e32 v80, v2
	v_mov_b32_e32 v81, v2
	v_mov_b32_e32 v90, v2
	v_mov_b32_e32 v91, v2
	v_mov_b32_e32 v92, v2
	v_mov_b32_e32 v93, v2
	v_mov_b32_e32 v94, v2
	v_mov_b32_e32 v95, v2
	v_mov_b32_e32 v96, v2
	v_mov_b32_e32 v97, v2
	v_mov_b32_e32 v106, v2
	v_mov_b32_e32 v107, v2
	v_mov_b32_e32 v108, v2
	v_mov_b32_e32 v109, v2
	v_mov_b32_e32 v110, v2
	v_mov_b32_e32 v111, v2
	v_mov_b32_e32 v112, v2
	v_mov_b32_e32 v113, v2
	v_mov_b32_e32 v122, v2
	v_mov_b32_e32 v123, v2
	v_mov_b32_e32 v124, v2
	v_mov_b32_e32 v125, v2
	v_mov_b32_e32 v126, v2
	v_mov_b32_e32 v127, v2
	v_mov_b32_e32 v128, v2
	v_mov_b32_e32 v129, v2
	s_and_b64 vcc, exec, s[6:7]
	s_cbranch_vccz .Lsp_p1
	s_setprio 1
.Lsp_p1:
.LBB0_277:
	ds_read_b128 v[148:151], v145
	ds_read_b128 v[152:155], v145 offset:1024
	ds_read_b128 v[156:159], v145 offset:2048
	ds_read_b128 v[160:163], v145 offset:3072
	ds_read_b128 v[166:169], v146
	ds_read_b128 v[170:173], v146 offset:1024
	ds_read_b128 v[174:177], v146 offset:2048
	ds_read_b128 v[178:181], v146 offset:3072
	s_add_u32 s28, s26, 0xfff80080
	s_addc_u32 s29, s27, -1
	s_cmp_eq_u32 s50, 28
	s_cselect_b32 s31, s2, s29
	s_cselect_b32 s30, s13, s28
	s_cselect_b32 s29, s15, s33
	s_cselect_b32 s28, s23, s25
	v_lshl_add_u64 v[214:215], s[26:27], 0, v[138:139]
	s_add_i32 m0, s37, 0xc000
	ds_read_b128 v[182:185], v147
	ds_read_b128 v[186:189], v147 offset:1024
	ds_read_b128 v[190:193], v147 offset:2048
	ds_read_b128 v[194:197], v147 offset:3072
	ds_read_b128 v[198:201], v147 offset:4096
	ds_read_b128 v[202:205], v147 offset:5120
	ds_read_b128 v[206:209], v147 offset:6144
	ds_read_b128 v[210:213], v147 offset:7168
	global_load_lds_dwordx4 v[214:215], off
	v_lshl_add_u64 v[214:215], s[26:27], 0, v[140:141]
	s_add_i32 m0, s37, 0xe000
	s_nop 0
	global_load_lds_dwordx4 v[214:215], off
	s_waitcnt vmcnt(8)
	s_waitcnt lgkmcnt(0)
	s_barrier
	s_nop 0
	s_waitcnt lgkmcnt(0)
	v_mfma_f32_16x16x32_bf16 v[126:129], v[148:151], v[182:185], v[126:129]
	v_mfma_f32_16x16x32_bf16 v[122:125], v[156:159], v[182:185], v[122:125]
	v_mfma_f32_16x16x32_bf16 v[110:113], v[148:151], v[190:193], v[110:113]
	v_mfma_f32_16x16x32_bf16 v[106:109], v[156:159], v[190:193], v[106:109]
	v_mfma_f32_16x16x32_bf16 v[94:97], v[148:151], v[198:201], v[94:97]
	v_mfma_f32_16x16x32_bf16 v[90:93], v[156:159], v[198:201], v[90:93]
	v_mfma_f32_16x16x32_bf16 v[78:81], v[148:151], v[206:209], v[78:81]
	v_mfma_f32_16x16x32_bf16 v[74:77], v[156:159], v[206:209], v[74:77]
	v_mfma_f32_16x16x32_bf16 v[126:129], v[152:155], v[186:189], v[126:129]
	v_mfma_f32_16x16x32_bf16 v[122:125], v[160:163], v[186:189], v[122:125]
	v_mfma_f32_16x16x32_bf16 v[110:113], v[152:155], v[194:197], v[110:113]
	v_mfma_f32_16x16x32_bf16 v[106:109], v[160:163], v[194:197], v[106:109]
	v_mfma_f32_16x16x32_bf16 v[94:97], v[152:155], v[202:205], v[94:97]
	v_mfma_f32_16x16x32_bf16 v[90:93], v[160:163], v[202:205], v[90:93]
	v_mfma_f32_16x16x32_bf16 v[78:81], v[152:155], v[210:213], v[78:81]
	v_mfma_f32_16x16x32_bf16 v[74:77], v[160:163], v[210:213], v[74:77]
	s_nop 0
	s_nop 0
	v_mfma_f32_16x16x32_bf16 v[118:121], v[166:169], v[182:185], v[118:121]
	v_mfma_f32_16x16x32_bf16 v[114:117], v[174:177], v[182:185], v[114:117]
	v_mfma_f32_16x16x32_bf16 v[102:105], v[166:169], v[190:193], v[102:105]
	v_mfma_f32_16x16x32_bf16 v[98:101], v[174:177], v[190:193], v[98:101]
	v_mfma_f32_16x16x32_bf16 v[86:89], v[166:169], v[198:201], v[86:89]
	v_mfma_f32_16x16x32_bf16 v[82:85], v[174:177], v[198:201], v[82:85]
	v_mfma_f32_16x16x32_bf16 v[70:73], v[166:169], v[206:209], v[70:73]
	v_mfma_f32_16x16x32_bf16 v[66:69], v[174:177], v[206:209], v[66:69]
	v_mfma_f32_16x16x32_bf16 v[118:121], v[170:173], v[186:189], v[118:121]
	v_mfma_f32_16x16x32_bf16 v[114:117], v[178:181], v[186:189], v[114:117]
	v_mfma_f32_16x16x32_bf16 v[102:105], v[170:173], v[194:197], v[102:105]
	v_mfma_f32_16x16x32_bf16 v[98:101], v[178:181], v[194:197], v[98:101]
	v_mfma_f32_16x16x32_bf16 v[86:89], v[170:173], v[202:205], v[86:89]
	v_mfma_f32_16x16x32_bf16 v[82:85], v[178:181], v[202:205], v[82:85]
	v_mfma_f32_16x16x32_bf16 v[70:73], v[170:173], v[210:213], v[70:73]
	v_mfma_f32_16x16x32_bf16 v[66:69], v[178:181], v[210:213], v[66:69]
	s_nop 0
	s_barrier
	s_add_i32 s51, s48, s36
	v_lshl_add_u64 v[214:215], s[28:29], 0, v[132:133]
	s_mov_b32 m0, s51
	ds_read_b128 v[182:185], v147 offset:16384
	ds_read_b128 v[186:189], v147 offset:17408
	ds_read_b128 v[190:193], v147 offset:18432
	ds_read_b128 v[194:197], v147 offset:19456
	ds_read_b128 v[198:201], v147 offset:20480
	ds_read_b128 v[202:205], v147 offset:21504
	ds_read_b128 v[206:209], v147 offset:22528
	ds_read_b128 v[210:213], v147 offset:23552
	global_load_lds_dwordx4 v[214:215], off
	s_add_i32 m0, s51, 0x2000
	s_add_u32 s52, s28, 0x80000
	v_lshl_add_u64 v[216:217], s[28:29], 0, v[136:137]
	s_addc_u32 s53, s29, 0
	s_add_i32 s51, s49, s36
	global_load_lds_dwordx4 v[216:217], off
	v_lshl_add_u64 v[218:219], s[52:53], 0, v[132:133]
	s_mov_b32 m0, s51
	v_lshl_add_u64 v[220:221], s[30:31], 0, v[134:135]
	global_load_lds_dwordx4 v[218:219], off
	v_lshl_add_u64 v[218:219], s[52:53], 0, v[136:137]
	s_add_i32 m0, s51, 0x2000
	s_nop 0
	global_load_lds_dwordx4 v[218:219], off
	v_lshl_add_u64 v[218:219], s[30:31], 0, v[130:131]
	s_mov_b32 m0, s37
	s_nop 0
	global_load_lds_dwordx4 v[218:219], off
	s_mov_b32 m0, s38
	s_nop 0
	global_load_lds_dwordx4 v[220:221], off
	s_waitcnt vmcnt(8)
	s_waitcnt lgkmcnt(0)
	s_barrier
	s_nop 0
	s_waitcnt lgkmcnt(0)
	v_mfma_f32_16x16x32_bf16 v[62:65], v[148:151], v[182:185], v[62:65]
	v_mfma_f32_16x16x32_bf16 v[58:61], v[156:159], v[182:185], v[58:61]
	v_mfma_f32_16x16x32_bf16 v[46:49], v[148:151], v[190:193], v[46:49]
	v_mfma_f32_16x16x32_bf16 v[42:45], v[156:159], v[190:193], v[42:45]
	v_mfma_f32_16x16x32_bf16 v[30:33], v[148:151], v[198:201], v[30:33]
	v_mfma_f32_16x16x32_bf16 v[26:29], v[156:159], v[198:201], v[26:29]
	v_mfma_f32_16x16x32_bf16 v[14:17], v[148:151], v[206:209], v[14:17]
	v_mfma_f32_16x16x32_bf16 v[10:13], v[156:159], v[206:209], v[10:13]
	v_mfma_f32_16x16x32_bf16 v[62:65], v[152:155], v[186:189], v[62:65]
	v_mfma_f32_16x16x32_bf16 v[58:61], v[160:163], v[186:189], v[58:61]
	v_mfma_f32_16x16x32_bf16 v[46:49], v[152:155], v[194:197], v[46:49]
	v_mfma_f32_16x16x32_bf16 v[42:45], v[160:163], v[194:197], v[42:45]
	v_mfma_f32_16x16x32_bf16 v[30:33], v[152:155], v[202:205], v[30:33]
	v_mfma_f32_16x16x32_bf16 v[26:29], v[160:163], v[202:205], v[26:29]
	v_mfma_f32_16x16x32_bf16 v[14:17], v[152:155], v[210:213], v[14:17]
	v_mfma_f32_16x16x32_bf16 v[10:13], v[160:163], v[210:213], v[10:13]
	s_nop 0
	s_nop 0
	v_mfma_f32_16x16x32_bf16 v[54:57], v[166:169], v[182:185], v[54:57]
	v_mfma_f32_16x16x32_bf16 v[50:53], v[174:177], v[182:185], v[50:53]
	v_mfma_f32_16x16x32_bf16 v[38:41], v[166:169], v[190:193], v[38:41]
	v_mfma_f32_16x16x32_bf16 v[34:37], v[174:177], v[190:193], v[34:37]
	v_mfma_f32_16x16x32_bf16 v[22:25], v[166:169], v[198:201], v[22:25]
	v_mfma_f32_16x16x32_bf16 v[18:21], v[174:177], v[198:201], v[18:21]
	v_mfma_f32_16x16x32_bf16 v[6:9], v[166:169], v[206:209], v[6:9]
	v_mfma_f32_16x16x32_bf16 v[2:5], v[174:177], v[206:209], v[2:5]
	v_mfma_f32_16x16x32_bf16 v[54:57], v[170:173], v[186:189], v[54:57]
	v_mfma_f32_16x16x32_bf16 v[50:53], v[178:181], v[186:189], v[50:53]
	v_mfma_f32_16x16x32_bf16 v[38:41], v[170:173], v[194:197], v[38:41]
	v_mfma_f32_16x16x32_bf16 v[34:37], v[178:181], v[194:197], v[34:37]
	v_mfma_f32_16x16x32_bf16 v[22:25], v[170:173], v[202:205], v[22:25]
	v_mfma_f32_16x16x32_bf16 v[18:21], v[178:181], v[202:205], v[18:21]
	v_mfma_f32_16x16x32_bf16 v[6:9], v[170:173], v[210:213], v[6:9]
	v_mfma_f32_16x16x32_bf16 v[2:5], v[178:181], v[210:213], v[2:5]
	s_nop 0
	s_barrier
	s_add_i32 s51, 0, 0x18000
	s_add_i32 s52, 0, 0x1c000
	v_add_u32_e32 v160, s51, v144
	v_add_u32_e32 v164, s52, v144
	ds_read_b128 v[148:151], v160
	ds_read_b128 v[152:155], v160 offset:1024
	ds_read_b128 v[156:159], v160 offset:2048
	ds_read_b128 v[160:163], v160 offset:3072
	ds_read_b128 v[166:169], v164
	ds_read_b128 v[170:173], v164 offset:1024
	ds_read_b128 v[174:177], v164 offset:2048
	ds_read_b128 v[178:181], v164 offset:3072
	s_add_u32 s30, s30, 0x80000
	s_addc_u32 s31, s31, 0
	s_mov_b32 m0, s39
	v_lshl_add_u64 v[222:223], s[30:31], 0, v[130:131]
	ds_read_b128 v[182:185], v147 offset:32768
	ds_read_b128 v[186:189], v147 offset:33792
	ds_read_b128 v[190:193], v147 offset:34816
	ds_read_b128 v[194:197], v147 offset:35840
	ds_read_b128 v[198:201], v147 offset:36864
	ds_read_b128 v[202:205], v147 offset:37888
	ds_read_b128 v[206:209], v147 offset:38912
	ds_read_b128 v[210:213], v147 offset:39936
	global_load_lds_dwordx4 v[222:223], off
	v_lshl_add_u64 v[222:223], s[30:31], 0, v[134:135]
	s_mov_b32 m0, s40
	s_nop 0
	global_load_lds_dwordx4 v[222:223], off
	s_waitcnt vmcnt(8)
	s_waitcnt lgkmcnt(0)
	s_barrier
	s_nop 0
	s_waitcnt lgkmcnt(0)
	v_mfma_f32_16x16x32_bf16 v[126:129], v[148:151], v[182:185], v[126:129]
	v_mfma_f32_16x16x32_bf16 v[122:125], v[156:159], v[182:185], v[122:125]
	v_mfma_f32_16x16x32_bf16 v[110:113], v[148:151], v[190:193], v[110:113]
	v_mfma_f32_16x16x32_bf16 v[106:109], v[156:159], v[190:193], v[106:109]
	v_mfma_f32_16x16x32_bf16 v[94:97], v[148:151], v[198:201], v[94:97]
	v_mfma_f32_16x16x32_bf16 v[90:93], v[156:159], v[198:201], v[90:93]
	v_mfma_f32_16x16x32_bf16 v[78:81], v[148:151], v[206:209], v[78:81]
	v_mfma_f32_16x16x32_bf16 v[74:77], v[156:159], v[206:209], v[74:77]
	v_mfma_f32_16x16x32_bf16 v[126:129], v[152:155], v[186:189], v[126:129]
	v_mfma_f32_16x16x32_bf16 v[122:125], v[160:163], v[186:189], v[122:125]
	v_mfma_f32_16x16x32_bf16 v[110:113], v[152:155], v[194:197], v[110:113]
	v_mfma_f32_16x16x32_bf16 v[106:109], v[160:163], v[194:197], v[106:109]
	v_mfma_f32_16x16x32_bf16 v[94:97], v[152:155], v[202:205], v[94:97]
	v_mfma_f32_16x16x32_bf16 v[90:93], v[160:163], v[202:205], v[90:93]
	v_mfma_f32_16x16x32_bf16 v[78:81], v[152:155], v[210:213], v[78:81]
	v_mfma_f32_16x16x32_bf16 v[74:77], v[160:163], v[210:213], v[74:77]
	s_nop 0
	s_nop 0
	v_mfma_f32_16x16x32_bf16 v[118:121], v[166:169], v[182:185], v[118:121]
	v_mfma_f32_16x16x32_bf16 v[114:117], v[174:177], v[182:185], v[114:117]
	v_mfma_f32_16x16x32_bf16 v[102:105], v[166:169], v[190:193], v[102:105]
	v_mfma_f32_16x16x32_bf16 v[98:101], v[174:177], v[190:193], v[98:101]
	v_mfma_f32_16x16x32_bf16 v[86:89], v[166:169], v[198:201], v[86:89]
	v_mfma_f32_16x16x32_bf16 v[82:85], v[174:177], v[198:201], v[82:85]
	v_mfma_f32_16x16x32_bf16 v[70:73], v[166:169], v[206:209], v[70:73]
	v_mfma_f32_16x16x32_bf16 v[66:69], v[174:177], v[206:209], v[66:69]
	v_mfma_f32_16x16x32_bf16 v[118:121], v[170:173], v[186:189], v[118:121]
	v_mfma_f32_16x16x32_bf16 v[114:117], v[178:181], v[186:189], v[114:117]
	v_mfma_f32_16x16x32_bf16 v[102:105], v[170:173], v[194:197], v[102:105]
	v_mfma_f32_16x16x32_bf16 v[98:101], v[178:181], v[194:197], v[98:101]
	v_mfma_f32_16x16x32_bf16 v[86:89], v[170:173], v[202:205], v[86:89]
	v_mfma_f32_16x16x32_bf16 v[82:85], v[178:181], v[202:205], v[82:85]
	v_mfma_f32_16x16x32_bf16 v[70:73], v[170:173], v[210:213], v[70:73]
	v_mfma_f32_16x16x32_bf16 v[66:69], v[178:181], v[210:213], v[66:69]
	s_nop 0
	s_barrier
	s_add_i32 s30, s51, s36
	v_lshl_add_u64 v[214:215], v[214:215], 0, s[8:9]
	s_mov_b32 m0, s30
	ds_read_b128 v[182:185], v147 offset:49152
	ds_read_b128 v[186:189], v147 offset:50176
	ds_read_b128 v[190:193], v147 offset:51200
	ds_read_b128 v[194:197], v147 offset:52224
	ds_read_b128 v[198:201], v147 offset:53248
	ds_read_b128 v[202:205], v147 offset:54272
	ds_read_b128 v[206:209], v147 offset:55296
	ds_read_b128 v[210:213], v147 offset:56320
	global_load_lds_dwordx4 v[214:215], off
	s_add_i32 m0, s30, 0x2000
	s_add_u32 s28, s28, 0x80080
	v_lshl_add_u64 v[214:215], v[216:217], 0, s[8:9]
	s_addc_u32 s29, s29, 0
	s_add_i32 s30, s52, s36
	global_load_lds_dwordx4 v[214:215], off
	v_lshl_add_u64 v[214:215], s[28:29], 0, v[132:133]
	s_mov_b32 m0, s30
	s_nop 0
	global_load_lds_dwordx4 v[214:215], off
	v_lshl_add_u64 v[214:215], s[28:29], 0, v[136:137]
	s_add_i32 m0, s30, 0x2000
	s_nop 0
	global_load_lds_dwordx4 v[214:215], off
	v_lshl_add_u64 v[214:215], v[218:219], 0, s[8:9]
	s_mov_b32 m0, s44
	s_nop 0
	global_load_lds_dwordx4 v[214:215], off
	v_lshl_add_u64 v[214:215], v[220:221], 0, s[8:9]
	s_mov_b32 m0, s45
	s_nop 0
	global_load_lds_dwordx4 v[214:215], off
	s_waitcnt vmcnt(8)
	s_waitcnt lgkmcnt(0)
	s_barrier
	s_nop 0
	s_waitcnt lgkmcnt(0)
	v_mfma_f32_16x16x32_bf16 v[62:65], v[148:151], v[182:185], v[62:65]
	v_mfma_f32_16x16x32_bf16 v[58:61], v[156:159], v[182:185], v[58:61]
	v_mfma_f32_16x16x32_bf16 v[46:49], v[148:151], v[190:193], v[46:49]
	v_mfma_f32_16x16x32_bf16 v[42:45], v[156:159], v[190:193], v[42:45]
	v_mfma_f32_16x16x32_bf16 v[30:33], v[148:151], v[198:201], v[30:33]
	v_mfma_f32_16x16x32_bf16 v[26:29], v[156:159], v[198:201], v[26:29]
	v_mfma_f32_16x16x32_bf16 v[14:17], v[148:151], v[206:209], v[14:17]
	v_mfma_f32_16x16x32_bf16 v[10:13], v[156:159], v[206:209], v[10:13]
	v_mfma_f32_16x16x32_bf16 v[62:65], v[152:155], v[186:189], v[62:65]
	v_mfma_f32_16x16x32_bf16 v[58:61], v[160:163], v[186:189], v[58:61]
	v_mfma_f32_16x16x32_bf16 v[46:49], v[152:155], v[194:197], v[46:49]
	v_mfma_f32_16x16x32_bf16 v[42:45], v[160:163], v[194:197], v[42:45]
	v_mfma_f32_16x16x32_bf16 v[30:33], v[152:155], v[202:205], v[30:33]
	v_mfma_f32_16x16x32_bf16 v[26:29], v[160:163], v[202:205], v[26:29]
	v_mfma_f32_16x16x32_bf16 v[14:17], v[152:155], v[210:213], v[14:17]
	v_mfma_f32_16x16x32_bf16 v[10:13], v[160:163], v[210:213], v[10:13]
	s_nop 0
	s_nop 0
	v_mfma_f32_16x16x32_bf16 v[54:57], v[166:169], v[182:185], v[54:57]
	v_mfma_f32_16x16x32_bf16 v[50:53], v[174:177], v[182:185], v[50:53]
	v_mfma_f32_16x16x32_bf16 v[38:41], v[166:169], v[190:193], v[38:41]
	v_mfma_f32_16x16x32_bf16 v[34:37], v[174:177], v[190:193], v[34:37]
	v_mfma_f32_16x16x32_bf16 v[22:25], v[166:169], v[198:201], v[22:25]
	v_mfma_f32_16x16x32_bf16 v[18:21], v[174:177], v[198:201], v[18:21]
	v_mfma_f32_16x16x32_bf16 v[6:9], v[166:169], v[206:209], v[6:9]
	v_mfma_f32_16x16x32_bf16 v[2:5], v[174:177], v[206:209], v[2:5]
	v_mfma_f32_16x16x32_bf16 v[54:57], v[170:173], v[186:189], v[54:57]
	v_mfma_f32_16x16x32_bf16 v[50:53], v[178:181], v[186:189], v[50:53]
	v_mfma_f32_16x16x32_bf16 v[38:41], v[170:173], v[194:197], v[38:41]
	v_mfma_f32_16x16x32_bf16 v[34:37], v[178:181], v[194:197], v[34:37]
	v_mfma_f32_16x16x32_bf16 v[22:25], v[170:173], v[202:205], v[22:25]
	v_mfma_f32_16x16x32_bf16 v[18:21], v[178:181], v[202:205], v[18:21]
	v_mfma_f32_16x16x32_bf16 v[6:9], v[170:173], v[210:213], v[6:9]
	v_mfma_f32_16x16x32_bf16 v[2:5], v[178:181], v[210:213], v[2:5]
	s_nop 0
	s_barrier
	s_add_i32 s50, s50, 2
	s_add_u32 s26, s26, 0x100
	s_addc_u32 s27, s27, 0
	s_add_u32 s25, s25, 0x100
	s_addc_u32 s33, s33, 0
	s_cmp_gt_u32 s50, 29
	s_cbranch_scc0 .LBB0_277
	s_setprio 0
	s_and_b64 vcc, exec, s[10:11]
	s_cbranch_vccz .LBB0_280
	s_barrier

.LBB0_1336:
	s_and_b64 s[34:35], s[0:1], exec
	s_cselect_b32 s17, s21, s29
	s_cselect_b32 s19, s20, s28
	s_cselect_b32 s50, s23, s31
	s_cselect_b32 s51, s22, s30
	s_add_u32 s28, s28, 0x80080
	s_addc_u32 s29, s29, 0
	s_add_u32 s52, s30, 0x100
	v_mov_b32_e32 v6, 0
	s_addc_u32 s53, s31, 0
	s_mov_b32 s54, -2
	v_mov_b32_e32 v7, v6
	v_mov_b32_e32 v8, v6
	v_mov_b32_e32 v9, v6
	v_mov_b32_e32 v14, v6
	v_mov_b32_e32 v15, v6
	v_mov_b32_e32 v16, v6
	v_mov_b32_e32 v17, v6
	v_mov_b32_e32 v22, v6
	v_mov_b32_e32 v23, v6
	v_mov_b32_e32 v24, v6
	v_mov_b32_e32 v25, v6
	v_mov_b32_e32 v30, v6
	v_mov_b32_e32 v31, v6
	v_mov_b32_e32 v32, v6
	v_mov_b32_e32 v33, v6
	v_mov_b32_e32 v38, v6
	v_mov_b32_e32 v39, v6
	v_mov_b32_e32 v40, v6
	v_mov_b32_e32 v41, v6
	v_mov_b32_e32 v46, v6
	v_mov_b32_e32 v47, v6
	v_mov_b32_e32 v48, v6
	v_mov_b32_e32 v49, v6
	v_mov_b32_e32 v54, v6
	v_mov_b32_e32 v55, v6
	v_mov_b32_e32 v56, v6
	v_mov_b32_e32 v57, v6
	v_mov_b32_e32 v62, v6
	v_mov_b32_e32 v63, v6
	v_mov_b32_e32 v64, v6
	v_mov_b32_e32 v65, v6
	v_mov_b32_e32 v2, v6
	v_mov_b32_e32 v3, v6
	v_mov_b32_e32 v4, v6
	v_mov_b32_e32 v5, v6
	v_mov_b32_e32 v10, v6
	v_mov_b32_e32 v11, v6
	v_mov_b32_e32 v12, v6
	v_mov_b32_e32 v13, v6
	v_mov_b32_e32 v18, v6
	v_mov_b32_e32 v19, v6
	v_mov_b32_e32 v20, v6
	v_mov_b32_e32 v21, v6
	v_mov_b32_e32 v26, v6
	v_mov_b32_e32 v27, v6
	v_mov_b32_e32 v28, v6
	v_mov_b32_e32 v29, v6
	v_mov_b32_e32 v34, v6
	v_mov_b32_e32 v35, v6
	v_mov_b32_e32 v36, v6
	v_mov_b32_e32 v37, v6
	v_mov_b32_e32 v42, v6
	v_mov_b32_e32 v43, v6
	v_mov_b32_e32 v44, v6
	v_mov_b32_e32 v45, v6
	v_mov_b32_e32 v50, v6
	v_mov_b32_e32 v51, v6
	v_mov_b32_e32 v52, v6
	v_mov_b32_e32 v53, v6
	v_mov_b32_e32 v58, v6
	v_mov_b32_e32 v59, v6
	v_mov_b32_e32 v60, v6
	v_mov_b32_e32 v61, v6
	v_mov_b32_e32 v70, v6
	v_mov_b32_e32 v71, v6
	v_mov_b32_e32 v72, v6
	v_mov_b32_e32 v73, v6
	v_mov_b32_e32 v78, v6
	v_mov_b32_e32 v79, v6
	v_mov_b32_e32 v80, v6
	v_mov_b32_e32 v81, v6
	v_mov_b32_e32 v86, v6
	v_mov_b32_e32 v87, v6
	v_mov_b32_e32 v88, v6
	v_mov_b32_e32 v89, v6
	v_mov_b32_e32 v94, v6
	v_mov_b32_e32 v95, v6
	v_mov_b32_e32 v96, v6
	v_mov_b32_e32 v97, v6
	v_mov_b32_e32 v102, v6
	v_mov_b32_e32 v103, v6
	v_mov_b32_e32 v104, v6
	v_mov_b32_e32 v105, v6
	v_mov_b32_e32 v110, v6
	v_mov_b32_e32 v111, v6
	v_mov_b32_e32 v112, v6
	v_mov_b32_e32 v113, v6
	v_mov_b32_e32 v118, v6
	v_mov_b32_e32 v119, v6
	v_mov_b32_e32 v120, v6
	v_mov_b32_e32 v121, v6
	v_mov_b32_e32 v126, v6
	v_mov_b32_e32 v127, v6
	v_mov_b32_e32 v128, v6
	v_mov_b32_e32 v129, v6
	v_mov_b32_e32 v66, v6
	v_mov_b32_e32 v67, v6
	v_mov_b32_e32 v68, v6
	v_mov_b32_e32 v69, v6
	v_mov_b32_e32 v74, v6
	v_mov_b32_e32 v75, v6
	v_mov_b32_e32 v76, v6
	v_mov_b32_e32 v77, v6
	v_mov_b32_e32 v82, v6
	v_mov_b32_e32 v83, v6
	v_mov_b32_e32 v84, v6
	v_mov_b32_e32 v85, v6
	v_mov_b32_e32 v90, v6
	v_mov_b32_e32 v91, v6
	v_mov_b32_e32 v92, v6
	v_mov_b32_e32 v93, v6
	v_mov_b32_e32 v98, v6
	v_mov_b32_e32 v99, v6
	v_mov_b32_e32 v100, v6
	v_mov_b32_e32 v101, v6
	v_mov_b32_e32 v106, v6
	v_mov_b32_e32 v107, v6
	v_mov_b32_e32 v108, v6
	v_mov_b32_e32 v109, v6
	v_mov_b32_e32 v114, v6
	v_mov_b32_e32 v115, v6
	v_mov_b32_e32 v116, v6
	v_mov_b32_e32 v117, v6
	v_mov_b32_e32 v122, v6
	v_mov_b32_e32 v123, v6
	v_mov_b32_e32 v124, v6
	v_mov_b32_e32 v125, v6
	s_and_b64 vcc, exec, s[8:9]
	s_cbranch_vccz .Lsp_p10
	s_setprio 1
.Lsp_p10:
.LBB0_1337:
	ds_read_b128 v[142:145], v149
	ds_read_b128 v[154:157], v149 offset:1024
	ds_read_b128 v[158:161], v149 offset:2048
	ds_read_b128 v[166:169], v149 offset:3072
	ds_read_b128 v[170:173], v150
	ds_read_b128 v[174:177], v150 offset:1024
	ds_read_b128 v[178:181], v150 offset:2048
	ds_read_b128 v[182:185], v150 offset:3072
	s_add_u32 s30, s28, 0xfff80080
	s_addc_u32 s31, s29, -1
	s_cmp_eq_u32 s54, 28
	s_cselect_b32 s35, s17, s31
	s_cselect_b32 s34, s19, s30
	s_cselect_b32 s31, s50, s53
	s_cselect_b32 s30, s51, s52
	v_lshl_add_u64 v[162:163], s[28:29], 0, v[138:139]
	s_add_i32 m0, s25, 0xc000
	ds_read_b128 v[186:189], v151
	ds_read_b128 v[190:193], v151 offset:1024
	ds_read_b128 v[194:197], v151 offset:2048
	ds_read_b128 v[198:201], v151 offset:3072
	ds_read_b128 v[202:205], v151 offset:4096
	ds_read_b128 v[206:209], v151 offset:5120
	ds_read_b128 v[210:213], v151 offset:6144
	ds_read_b128 v[214:217], v151 offset:7168
	global_load_lds_dwordx4 v[162:163], off
	v_lshl_add_u64 v[162:163], s[28:29], 0, v[140:141]
	s_add_i32 m0, s25, 0xe000
	s_nop 0
	global_load_lds_dwordx4 v[162:163], off
	s_waitcnt vmcnt(8)
	s_waitcnt lgkmcnt(0)
	s_barrier
	s_nop 0
	s_waitcnt lgkmcnt(0)
	v_mfma_f32_16x16x32_bf16 v[122:125], v[142:145], v[186:189], v[122:125]
	v_mfma_f32_16x16x32_bf16 v[114:117], v[158:161], v[186:189], v[114:117]
	v_mfma_f32_16x16x32_bf16 v[106:109], v[142:145], v[194:197], v[106:109]
	v_mfma_f32_16x16x32_bf16 v[98:101], v[158:161], v[194:197], v[98:101]
	v_mfma_f32_16x16x32_bf16 v[90:93], v[142:145], v[202:205], v[90:93]
	v_mfma_f32_16x16x32_bf16 v[82:85], v[158:161], v[202:205], v[82:85]
	v_mfma_f32_16x16x32_bf16 v[74:77], v[142:145], v[210:213], v[74:77]
	v_mfma_f32_16x16x32_bf16 v[66:69], v[158:161], v[210:213], v[66:69]
	v_mfma_f32_16x16x32_bf16 v[122:125], v[154:157], v[190:193], v[122:125]
	v_mfma_f32_16x16x32_bf16 v[114:117], v[166:169], v[190:193], v[114:117]
	v_mfma_f32_16x16x32_bf16 v[106:109], v[154:157], v[198:201], v[106:109]
	v_mfma_f32_16x16x32_bf16 v[98:101], v[166:169], v[198:201], v[98:101]
	v_mfma_f32_16x16x32_bf16 v[90:93], v[154:157], v[206:209], v[90:93]
	v_mfma_f32_16x16x32_bf16 v[82:85], v[166:169], v[206:209], v[82:85]
	v_mfma_f32_16x16x32_bf16 v[74:77], v[154:157], v[214:217], v[74:77]
	v_mfma_f32_16x16x32_bf16 v[66:69], v[166:169], v[214:217], v[66:69]
	s_nop 0
	s_nop 0
	v_mfma_f32_16x16x32_bf16 v[126:129], v[170:173], v[186:189], v[126:129]
	v_mfma_f32_16x16x32_bf16 v[118:121], v[178:181], v[186:189], v[118:121]
	v_mfma_f32_16x16x32_bf16 v[110:113], v[170:173], v[194:197], v[110:113]
	v_mfma_f32_16x16x32_bf16 v[102:105], v[178:181], v[194:197], v[102:105]
	v_mfma_f32_16x16x32_bf16 v[94:97], v[170:173], v[202:205], v[94:97]
	v_mfma_f32_16x16x32_bf16 v[86:89], v[178:181], v[202:205], v[86:89]
	v_mfma_f32_16x16x32_bf16 v[78:81], v[170:173], v[210:213], v[78:81]
	v_mfma_f32_16x16x32_bf16 v[70:73], v[178:181], v[210:213], v[70:73]
	v_mfma_f32_16x16x32_bf16 v[126:129], v[174:177], v[190:193], v[126:129]
	v_mfma_f32_16x16x32_bf16 v[118:121], v[182:185], v[190:193], v[118:121]
	v_mfma_f32_16x16x32_bf16 v[110:113], v[174:177], v[198:201], v[110:113]
	v_mfma_f32_16x16x32_bf16 v[102:105], v[182:185], v[198:201], v[102:105]
	v_mfma_f32_16x16x32_bf16 v[94:97], v[174:177], v[206:209], v[94:97]
	v_mfma_f32_16x16x32_bf16 v[86:89], v[182:185], v[206:209], v[86:89]
	v_mfma_f32_16x16x32_bf16 v[78:81], v[174:177], v[214:217], v[78:81]
	v_mfma_f32_16x16x32_bf16 v[70:73], v[182:185], v[214:217], v[70:73]
	s_nop 0
	s_barrier
	s_add_i32 s55, s46, s36
	v_lshl_add_u64 v[162:163], s[30:31], 0, v[132:133]
	s_mov_b32 m0, s55
	ds_read_b128 v[186:189], v151 offset:16384
	ds_read_b128 v[190:193], v151 offset:17408
	ds_read_b128 v[194:197], v151 offset:18432
	ds_read_b128 v[198:201], v151 offset:19456
	ds_read_b128 v[202:205], v151 offset:20480
	ds_read_b128 v[206:209], v151 offset:21504
	ds_read_b128 v[210:213], v151 offset:22528
	ds_read_b128 v[214:217], v151 offset:23552
	global_load_lds_dwordx4 v[162:163], off
	s_add_i32 m0, s55, 0x2000
	s_add_u32 s56, s30, 0x80000
	v_lshl_add_u64 v[218:219], s[30:31], 0, v[136:137]
	s_addc_u32 s57, s31, 0
	s_add_i32 s55, s47, s36
	global_load_lds_dwordx4 v[218:219], off
	v_lshl_add_u64 v[220:221], s[56:57], 0, v[132:133]
	s_mov_b32 m0, s55
	v_lshl_add_u64 v[222:223], s[34:35], 0, v[134:135]
	global_load_lds_dwordx4 v[220:221], off
	v_lshl_add_u64 v[220:221], s[56:57], 0, v[136:137]
	s_add_i32 m0, s55, 0x2000
	s_nop 0
	global_load_lds_dwordx4 v[220:221], off
	v_lshl_add_u64 v[220:221], s[34:35], 0, v[130:131]
	s_mov_b32 m0, s25
	s_nop 0
	global_load_lds_dwordx4 v[220:221], off
	s_mov_b32 m0, s27
	s_nop 0
	global_load_lds_dwordx4 v[222:223], off
	s_waitcnt vmcnt(8)
	s_waitcnt lgkmcnt(0)
	s_barrier
	s_nop 0
	s_waitcnt lgkmcnt(0)
	v_mfma_f32_16x16x32_bf16 v[58:61], v[142:145], v[186:189], v[58:61]
	v_mfma_f32_16x16x32_bf16 v[50:53], v[158:161], v[186:189], v[50:53]
	v_mfma_f32_16x16x32_bf16 v[42:45], v[142:145], v[194:197], v[42:45]
	v_mfma_f32_16x16x32_bf16 v[34:37], v[158:161], v[194:197], v[34:37]
	v_mfma_f32_16x16x32_bf16 v[26:29], v[142:145], v[202:205], v[26:29]
	v_mfma_f32_16x16x32_bf16 v[18:21], v[158:161], v[202:205], v[18:21]
	v_mfma_f32_16x16x32_bf16 v[10:13], v[142:145], v[210:213], v[10:13]
	v_mfma_f32_16x16x32_bf16 v[2:5], v[158:161], v[210:213], v[2:5]
	v_mfma_f32_16x16x32_bf16 v[58:61], v[154:157], v[190:193], v[58:61]
	v_mfma_f32_16x16x32_bf16 v[50:53], v[166:169], v[190:193], v[50:53]
	v_mfma_f32_16x16x32_bf16 v[42:45], v[154:157], v[198:201], v[42:45]
	v_mfma_f32_16x16x32_bf16 v[34:37], v[166:169], v[198:201], v[34:37]
	v_mfma_f32_16x16x32_bf16 v[26:29], v[154:157], v[206:209], v[26:29]
	v_mfma_f32_16x16x32_bf16 v[18:21], v[166:169], v[206:209], v[18:21]
	v_mfma_f32_16x16x32_bf16 v[10:13], v[154:157], v[214:217], v[10:13]
	v_mfma_f32_16x16x32_bf16 v[2:5], v[166:169], v[214:217], v[2:5]
	s_nop 0
	s_nop 0
	v_mfma_f32_16x16x32_bf16 v[62:65], v[170:173], v[186:189], v[62:65]
	v_mfma_f32_16x16x32_bf16 v[54:57], v[178:181], v[186:189], v[54:57]
	v_mfma_f32_16x16x32_bf16 v[46:49], v[170:173], v[194:197], v[46:49]
	v_mfma_f32_16x16x32_bf16 v[38:41], v[178:181], v[194:197], v[38:41]
	v_mfma_f32_16x16x32_bf16 v[30:33], v[170:173], v[202:205], v[30:33]
	v_mfma_f32_16x16x32_bf16 v[22:25], v[178:181], v[202:205], v[22:25]
	v_mfma_f32_16x16x32_bf16 v[14:17], v[170:173], v[210:213], v[14:17]
	v_mfma_f32_16x16x32_bf16 v[6:9], v[178:181], v[210:213], v[6:9]
	v_mfma_f32_16x16x32_bf16 v[62:65], v[174:177], v[190:193], v[62:65]
	v_mfma_f32_16x16x32_bf16 v[54:57], v[182:185], v[190:193], v[54:57]
	v_mfma_f32_16x16x32_bf16 v[46:49], v[174:177], v[198:201], v[46:49]
	v_mfma_f32_16x16x32_bf16 v[38:41], v[182:185], v[198:201], v[38:41]
	v_mfma_f32_16x16x32_bf16 v[30:33], v[174:177], v[206:209], v[30:33]
	v_mfma_f32_16x16x32_bf16 v[22:25], v[182:185], v[206:209], v[22:25]
	v_mfma_f32_16x16x32_bf16 v[14:17], v[174:177], v[214:217], v[14:17]
	v_mfma_f32_16x16x32_bf16 v[6:9], v[182:185], v[214:217], v[6:9]
	s_nop 0
	s_barrier
	s_add_i32 s55, 0, 0x18000
	v_add_u32_e32 v153, s55, v148
	s_add_i32 s56, 0, 0x1c000
	ds_read_b128 v[142:145], v153
	ds_read_b128 v[154:157], v153 offset:1024
	ds_read_b128 v[158:161], v153 offset:2048
	ds_read_b128 v[166:169], v153 offset:3072
	v_add_u32_e32 v153, s56, v148
	ds_read_b128 v[170:173], v153
	ds_read_b128 v[174:177], v153 offset:1024
	ds_read_b128 v[178:181], v153 offset:2048
	ds_read_b128 v[182:185], v153 offset:3072
	s_add_u32 s34, s34, 0x80000
	s_addc_u32 s35, s35, 0
	s_mov_b32 m0, s37
	v_lshl_add_u64 v[224:225], s[34:35], 0, v[130:131]
	ds_read_b128 v[186:189], v151 offset:32768
	ds_read_b128 v[190:193], v151 offset:33792
	ds_read_b128 v[194:197], v151 offset:34816
	ds_read_b128 v[198:201], v151 offset:35840
	ds_read_b128 v[202:205], v151 offset:36864
	ds_read_b128 v[206:209], v151 offset:37888
	ds_read_b128 v[210:213], v151 offset:38912
	ds_read_b128 v[214:217], v151 offset:39936
	global_load_lds_dwordx4 v[224:225], off
	v_lshl_add_u64 v[224:225], s[34:35], 0, v[134:135]
	s_mov_b32 m0, s38
	s_nop 0
	global_load_lds_dwordx4 v[224:225], off
	s_waitcnt vmcnt(8)
	s_waitcnt lgkmcnt(0)
	s_barrier
	s_nop 0
	s_waitcnt lgkmcnt(0)
	v_mfma_f32_16x16x32_bf16 v[122:125], v[142:145], v[186:189], v[122:125]
	v_mfma_f32_16x16x32_bf16 v[114:117], v[158:161], v[186:189], v[114:117]
	v_mfma_f32_16x16x32_bf16 v[106:109], v[142:145], v[194:197], v[106:109]
	v_mfma_f32_16x16x32_bf16 v[98:101], v[158:161], v[194:197], v[98:101]
	v_mfma_f32_16x16x32_bf16 v[90:93], v[142:145], v[202:205], v[90:93]
	v_mfma_f32_16x16x32_bf16 v[82:85], v[158:161], v[202:205], v[82:85]
	v_mfma_f32_16x16x32_bf16 v[74:77], v[142:145], v[210:213], v[74:77]
	v_mfma_f32_16x16x32_bf16 v[66:69], v[158:161], v[210:213], v[66:69]
	v_mfma_f32_16x16x32_bf16 v[122:125], v[154:157], v[190:193], v[122:125]
	v_mfma_f32_16x16x32_bf16 v[114:117], v[166:169], v[190:193], v[114:117]
	v_mfma_f32_16x16x32_bf16 v[106:109], v[154:157], v[198:201], v[106:109]
	v_mfma_f32_16x16x32_bf16 v[98:101], v[166:169], v[198:201], v[98:101]
	v_mfma_f32_16x16x32_bf16 v[90:93], v[154:157], v[206:209], v[90:93]
	v_mfma_f32_16x16x32_bf16 v[82:85], v[166:169], v[206:209], v[82:85]
	v_mfma_f32_16x16x32_bf16 v[74:77], v[154:157], v[214:217], v[74:77]
	v_mfma_f32_16x16x32_bf16 v[66:69], v[166:169], v[214:217], v[66:69]
	s_nop 0
	s_nop 0
	v_mfma_f32_16x16x32_bf16 v[126:129], v[170:173], v[186:189], v[126:129]
	v_mfma_f32_16x16x32_bf16 v[118:121], v[178:181], v[186:189], v[118:121]
	v_mfma_f32_16x16x32_bf16 v[110:113], v[170:173], v[194:197], v[110:113]
	v_mfma_f32_16x16x32_bf16 v[102:105], v[178:181], v[194:197], v[102:105]
	v_mfma_f32_16x16x32_bf16 v[94:97], v[170:173], v[202:205], v[94:97]
	v_mfma_f32_16x16x32_bf16 v[86:89], v[178:181], v[202:205], v[86:89]
	v_mfma_f32_16x16x32_bf16 v[78:81], v[170:173], v[210:213], v[78:81]
	v_mfma_f32_16x16x32_bf16 v[70:73], v[178:181], v[210:213], v[70:73]
	v_mfma_f32_16x16x32_bf16 v[126:129], v[174:177], v[190:193], v[126:129]
	v_mfma_f32_16x16x32_bf16 v[118:121], v[182:185], v[190:193], v[118:121]
	v_mfma_f32_16x16x32_bf16 v[110:113], v[174:177], v[198:201], v[110:113]
	v_mfma_f32_16x16x32_bf16 v[102:105], v[182:185], v[198:201], v[102:105]
	v_mfma_f32_16x16x32_bf16 v[94:97], v[174:177], v[206:209], v[94:97]
	v_mfma_f32_16x16x32_bf16 v[86:89], v[182:185], v[206:209], v[86:89]
	v_mfma_f32_16x16x32_bf16 v[78:81], v[174:177], v[214:217], v[78:81]
	v_mfma_f32_16x16x32_bf16 v[70:73], v[182:185], v[214:217], v[70:73]
	s_nop 0
	s_barrier
	s_add_i32 s34, s55, s36
	v_lshl_add_u64 v[162:163], v[162:163], 0, s[12:13]
	s_mov_b32 m0, s34
	ds_read_b128 v[186:189], v151 offset:49152
	ds_read_b128 v[190:193], v151 offset:50176
	ds_read_b128 v[194:197], v151 offset:51200
	ds_read_b128 v[198:201], v151 offset:52224
	ds_read_b128 v[202:205], v151 offset:53248
	ds_read_b128 v[206:209], v151 offset:54272
	ds_read_b128 v[210:213], v151 offset:55296
	ds_read_b128 v[214:217], v151 offset:56320
	global_load_lds_dwordx4 v[162:163], off
	s_add_i32 m0, s34, 0x2000
	s_add_u32 s30, s30, 0x80080
	v_lshl_add_u64 v[162:163], v[218:219], 0, s[12:13]
	s_addc_u32 s31, s31, 0
	s_add_i32 s34, s56, s36
	global_load_lds_dwordx4 v[162:163], off
	v_lshl_add_u64 v[162:163], s[30:31], 0, v[132:133]
	s_mov_b32 m0, s34
	s_nop 0
	global_load_lds_dwordx4 v[162:163], off
	v_lshl_add_u64 v[162:163], s[30:31], 0, v[136:137]
	s_add_i32 m0, s34, 0x2000
	s_nop 0
	global_load_lds_dwordx4 v[162:163], off
	v_lshl_add_u64 v[162:163], v[220:221], 0, s[12:13]
	s_mov_b32 m0, s42
	s_nop 0
	global_load_lds_dwordx4 v[162:163], off
	v_lshl_add_u64 v[162:163], v[222:223], 0, s[12:13]
	s_mov_b32 m0, s43
	s_nop 0
	global_load_lds_dwordx4 v[162:163], off
	s_waitcnt vmcnt(8)
	s_waitcnt lgkmcnt(0)
	s_barrier
	s_nop 0
	s_waitcnt lgkmcnt(0)
	v_mfma_f32_16x16x32_bf16 v[58:61], v[142:145], v[186:189], v[58:61]
	v_mfma_f32_16x16x32_bf16 v[50:53], v[158:161], v[186:189], v[50:53]
	v_mfma_f32_16x16x32_bf16 v[42:45], v[142:145], v[194:197], v[42:45]
	v_mfma_f32_16x16x32_bf16 v[34:37], v[158:161], v[194:197], v[34:37]
	v_mfma_f32_16x16x32_bf16 v[26:29], v[142:145], v[202:205], v[26:29]
	v_mfma_f32_16x16x32_bf16 v[18:21], v[158:161], v[202:205], v[18:21]
	v_mfma_f32_16x16x32_bf16 v[10:13], v[142:145], v[210:213], v[10:13]
	v_mfma_f32_16x16x32_bf16 v[2:5], v[158:161], v[210:213], v[2:5]
	v_mfma_f32_16x16x32_bf16 v[58:61], v[154:157], v[190:193], v[58:61]
	v_mfma_f32_16x16x32_bf16 v[50:53], v[166:169], v[190:193], v[50:53]
	v_mfma_f32_16x16x32_bf16 v[42:45], v[154:157], v[198:201], v[42:45]
	v_mfma_f32_16x16x32_bf16 v[34:37], v[166:169], v[198:201], v[34:37]
	v_mfma_f32_16x16x32_bf16 v[26:29], v[154:157], v[206:209], v[26:29]
	v_mfma_f32_16x16x32_bf16 v[18:21], v[166:169], v[206:209], v[18:21]
	v_mfma_f32_16x16x32_bf16 v[10:13], v[154:157], v[214:217], v[10:13]
	v_mfma_f32_16x16x32_bf16 v[2:5], v[166:169], v[214:217], v[2:5]
	s_nop 0
	s_nop 0
	v_mfma_f32_16x16x32_bf16 v[62:65], v[170:173], v[186:189], v[62:65]
	v_mfma_f32_16x16x32_bf16 v[54:57], v[178:181], v[186:189], v[54:57]
	v_mfma_f32_16x16x32_bf16 v[46:49], v[170:173], v[194:197], v[46:49]
	v_mfma_f32_16x16x32_bf16 v[38:41], v[178:181], v[194:197], v[38:41]
	v_mfma_f32_16x16x32_bf16 v[30:33], v[170:173], v[202:205], v[30:33]
	v_mfma_f32_16x16x32_bf16 v[22:25], v[178:181], v[202:205], v[22:25]
	v_mfma_f32_16x16x32_bf16 v[14:17], v[170:173], v[210:213], v[14:17]
	v_mfma_f32_16x16x32_bf16 v[6:9], v[178:181], v[210:213], v[6:9]
	v_mfma_f32_16x16x32_bf16 v[62:65], v[174:177], v[190:193], v[62:65]
	v_mfma_f32_16x16x32_bf16 v[54:57], v[182:185], v[190:193], v[54:57]
	v_mfma_f32_16x16x32_bf16 v[46:49], v[174:177], v[198:201], v[46:49]
	v_mfma_f32_16x16x32_bf16 v[38:41], v[182:185], v[198:201], v[38:41]
	v_mfma_f32_16x16x32_bf16 v[30:33], v[174:177], v[206:209], v[30:33]
	v_mfma_f32_16x16x32_bf16 v[22:25], v[182:185], v[206:209], v[22:25]
	v_mfma_f32_16x16x32_bf16 v[14:17], v[174:177], v[214:217], v[14:17]
	v_mfma_f32_16x16x32_bf16 v[6:9], v[182:185], v[214:217], v[6:9]
	s_nop 0
	s_barrier
	s_add_i32 s54, s54, 2
	s_add_u32 s28, s28, 0x100
	s_addc_u32 s29, s29, 0
	s_add_u32 s52, s52, 0x100
	s_addc_u32 s53, s53, 0
	s_cmp_gt_u32 s54, 29
	s_cbranch_scc0 .LBB0_1337
	s_setprio 0
	v_mov_b32_e32 v142, v1
	v_mov_b32_e32 v153, v147
	v_mov_b32_e32 v143, v165
	v_mov_b32_e32 v144, v146
	s_lshl_b32 s17, s26, 8
	s_add_i32 s17, s17, s40
	v_add_u32_e32 v142, s17, v144
	v_ashrrev_i32_e32 v143, 31, v142
	v_lshl_add_u64 v[144:145], v[142:143], 2, s[10:11]
	global_load_dword v229, v[144:145], off
	global_load_dword v230, v[144:145], off offset:64
	global_load_dword v231, v[144:145], off offset:128
	global_load_dword v232, v[144:145], off offset:192
	global_load_dword v233, v[144:145], off offset:512
	global_load_dword v234, v[144:145], off offset:576
	global_load_dword v235, v[144:145], off offset:640
	global_load_dword v236, v[144:145], off offset:704
	s_and_b64 vcc, exec, s[14:15]
	s_cbranch_vccz .LBB0_1340
	s_barrier
